# v015 + G4 epilogue: x1 tile preloaded into the accumulators before the K loop (no loads in phase 1), phase 2 issues all sum-of-squares loads before any store
# baseline (speedup 1.0000x reference)
; #define PG8_STAGE(bufoff, gbase, voff) do { _Pragma("unroll") for (int _i = 0; _i < 2; ++_i) \
;         __builtin_amdgcn_global_load_lds((const unsigned*)((const char*)(gbase) + (voff)[_i]), (LAS unsigned*)(lds + (bufoff) + ldsw + _i * 8192), 16, 0, 0); } while (0)
; #define PG8_WAIT_V(n) asm volatile("s_waitcnt vmcnt(" #n ")" ::: "memory")
; #define PG8_BAR __builtin_amdgcn_s_barrier()
; template <class Epi, class Sched, bool ALIGN_EPI = true>
; __device__ __forceinline__ void gemm_phase(LAS unsigned char* lds, const Gemm g, const Sched& S, const Epi& E) {
;     ...
;     const char* cA = (const char*)g.A + (size_t)cur.pm * tstep; const char* cB = (const char*)g.Bt + (size_t)cur.pn * tstep;
;     S.a_ready(cur);
;     PG8_STAGE(PG8_SB(0, 0), cB, voffB); PG8_STAGE(PG8_SB(0, 1), cB + hstep, voffB); PG8_STAGE(PG8_SA(0, 0), cA, voffA); PG8_STAGE(PG8_SA(0, 1), cA + hstep, voffA);
;     if (wr == 1) PG8_BAR;
;     PG8_WAIT_V(2); PG8_BAR;
;     PG8_STAGE(PG8_SB(1, 0), cB + kstep, voffB); PG8_STAGE(PG8_SA(1, 0), cA + kstep, voffA); PG8_STAGE(PG8_SB(1, 1), cB + hstep + kstep, voffB);
;     PG8_WAIT_V(6); PG8_BAR;
;     __device__ __forceinline__ void operator()(f32x4 (&acc)[2][2][4][2], const pg8::Unit& u, int wr, int wc, int fr, int fq) const {
;     ...
;                 const float* xr = oy + (size_t)row * DM + col0;
;                 float q = 0.f;
; #pragma unroll
;                 for (int bj = 0; bj < 2; ++bj)
; #pragma unroll
;                     for (int n = 0; n < 2; ++n) {
;                         const f32x4 o = *(const f32x4*)(xr + bj * 128 + n * 16) + acc[ai][bj][m][n];
.LBB0_844:
	s_or_b64 exec, exec, s[2:3]
	s_waitcnt vmcnt(1)
	s_lshr_b32 s88, s16, 8
	s_lshl_b32 s88, s88, 6
	s_lshl_b32 s89, s44, 8
	s_add_i32 s88, s88, s89
	v_and_b32_e32 v220, 15, v8
	v_add_u32_e32 v220, s88, v220
	v_mov_b32_e32 v221, 0
	v_lshlrev_b64 v[220:221], 13, v[220:221]
	s_bfe_u32 s88, s16, 0x20006
	s_lshl_b32 s88, s88, 5
	s_lshl_b32 s89, s10, 8
	s_add_i32 s88, s88, s89
	v_bfe_u32 v222, v8, 4, 2
	v_lshl_add_u32 v222, v222, 2, s88
	v_mov_b32_e32 v223, 0
	v_lshl_add_u64 v[220:221], s[84:85], 0, v[220:221]
	v_lshl_add_u64 v[220:221], v[222:223], 2, v[220:221]
	global_load_dwordx4 v[124:127], v[220:221], off
	global_load_dwordx4 v[120:123], v[220:221], off offset:64
	global_load_dwordx4 v[92:95], v[220:221], off offset:512
	global_load_dwordx4 v[88:91], v[220:221], off offset:576
	s_mov_b64 s[88:89], 0x20000
	v_lshl_add_u64 v[226:227], v[220:221], 0, s[88:89]
	global_load_dwordx4 v[116:119], v[226:227], off
	global_load_dwordx4 v[112:115], v[226:227], off offset:64
	global_load_dwordx4 v[84:87], v[226:227], off offset:512
	global_load_dwordx4 v[80:83], v[226:227], off offset:576
	s_mov_b64 s[88:89], 0x40000
	v_lshl_add_u64 v[224:225], v[220:221], 0, s[88:89]
	global_load_dwordx4 v[108:111], v[224:225], off
	global_load_dwordx4 v[104:107], v[224:225], off offset:64
	global_load_dwordx4 v[76:79], v[224:225], off offset:512
	global_load_dwordx4 v[72:75], v[224:225], off offset:576
	s_mov_b64 s[88:89], 0x60000
	v_lshl_add_u64 v[226:227], v[220:221], 0, s[88:89]
	global_load_dwordx4 v[100:103], v[226:227], off
	global_load_dwordx4 v[96:99], v[226:227], off offset:64
	global_load_dwordx4 v[68:71], v[226:227], off offset:512
	global_load_dwordx4 v[64:67], v[226:227], off offset:576
	s_mov_b64 s[88:89], 0x100000
	v_lshl_add_u64 v[224:225], v[220:221], 0, s[88:89]
	global_load_dwordx4 v[60:63], v[224:225], off
	global_load_dwordx4 v[56:59], v[224:225], off offset:64
	global_load_dwordx4 v[28:31], v[224:225], off offset:512
	global_load_dwordx4 v[24:27], v[224:225], off offset:576
	s_mov_b64 s[88:89], 0x120000
	v_lshl_add_u64 v[226:227], v[220:221], 0, s[88:89]
	global_load_dwordx4 v[52:55], v[226:227], off
	global_load_dwordx4 v[48:51], v[226:227], off offset:64
	global_load_dwordx4 v[20:23], v[226:227], off offset:512
	global_load_dwordx4 v[16:19], v[226:227], off offset:576
	s_mov_b64 s[88:89], 0x140000
	v_lshl_add_u64 v[224:225], v[220:221], 0, s[88:89]
	global_load_dwordx4 v[44:47], v[224:225], off
	global_load_dwordx4 v[40:43], v[224:225], off offset:64
	global_load_dwordx4 v[12:15], v[224:225], off offset:512
	global_load_dwordx4 v[208:211], v[224:225], off offset:576
	s_mov_b64 s[88:89], 0x160000
	v_lshl_add_u64 v[226:227], v[220:221], 0, s[88:89]
	global_load_dwordx4 v[36:39], v[226:227], off
	global_load_dwordx4 v[32:35], v[226:227], off offset:64
	global_load_dwordx4 v[212:215], v[226:227], off offset:512
	global_load_dwordx4 v[216:219], v[226:227], off offset:576
	v_bfe_i32 v2, v8, 27, 1
	v_lshlrev_b32_e32 v0, 4, v8
	v_lshrrev_b32_e32 v2, 22, v2
	v_add_u32_e32 v2, v0, v2
	v_and_b32_e32 v2, 0xfffffc00, v2
	v_sub_u32_e32 v2, v0, v2
	v_lshrrev_b32_e32 v3, 4, v2
	v_bitop3_b32 v2, v3, v2, 32 bitop3:0x6c
	s_waitcnt lgkmcnt(0)
	v_ashrrev_i32_e32 v1, 31, v8
	v_ashrrev_i32_e32 v4, 31, v2
	v_lshrrev_b32_e32 v1, 26, v1
	v_lshrrev_b32_e32 v4, 26, v4
	v_add_u32_e32 v1, v8, v1
	v_add_u32_e32 v4, v2, v4
	v_ashrrev_i32_e32 v1, 6, v1
	v_lshrrev_b32_e32 v5, 6, v4
	v_and_b32_e32 v4, 0xc0, v4
	v_lshlrev_b32_e32 v3, 3, v1
	v_lshlrev_b32_e32 v1, 5, v1
	v_sub_u32_e32 v2, v2, v4
	v_mov_b32_e32 v4, 1
	v_and_b32_e32 v3, 0xffff0, v3
	v_and_b32_e32 v1, 32, v1
	v_ashrrev_i16_sdwa v2, v4, sext(v2) dst_sel:DWORD dst_unused:UNUSED_PAD src0_sel:DWORD src1_sel:BYTE_0
	v_add_u32_sdwa v1, v1, sext(v2) dst_sel:DWORD dst_unused:UNUSED_PAD src0_sel:DWORD src1_sel:WORD_0
	v_add_lshl_u32 v2, v5, v3, 12
	v_add_u32_e32 v0, 0x2000, v0
	v_lshl_add_u32 v144, v1, 1, v2
	v_ashrrev_i32_e32 v1, 31, v0
	v_lshrrev_b32_e32 v1, 22, v1
	v_add_u32_e32 v1, v0, v1
	v_ashrrev_i32_e32 v1, 10, v1
	v_mul_i32_i24_e32 v2, 0x400, v1
	s_lshl_b32 s2, s44, 20
	v_readlane_b32 s4, v234, 25
	v_sub_u32_e32 v0, v0, v2
	v_readlane_b32 s5, v234, 26
	s_add_u32 s12, s4, s2
	v_lshrrev_b32_e32 v2, 4, v0
	s_addc_u32 s13, s5, 0
	s_ashr_i32 s11, s10, 31
	v_bitop3_b32 v0, v2, v0, 32 bitop3:0x6c
	s_lshl_b64 s[2:3], s[10:11], 20
	v_readlane_b32 s4, v234, 27
	v_ashrrev_i32_e32 v3, 31, v0
	v_readlane_b32 s5, v234, 28
	s_add_u32 s14, s4, s2
	v_lshrrev_b32_e32 v3, 26, v3
	s_addc_u32 s15, s5, s3
	s_ashr_i32 s2, s16, 6
	v_add_u32_e32 v3, v0, v3
	v_lshrrev_b32_e32 v5, 6, v3
	v_and_b32_e32 v3, 0xc0, v3
	s_lshl_b32 s11, s2, 10
	v_lshlrev_b32_e32 v2, 3, v1
	v_lshlrev_b32_e32 v1, 5, v1
	v_sub_u32_e32 v0, v0, v3
	s_add_i32 s45, s11, 0
	v_and_b32_e32 v2, 0xffff0, v2
	v_and_b32_e32 v1, 32, v1
	v_ashrrev_i16_sdwa v0, v4, sext(v0) dst_sel:DWORD dst_unused:UNUSED_PAD src0_sel:DWORD src1_sel:BYTE_0
	s_barrier
	s_add_i32 m0, s45, 0x10000
	v_add_u32_sdwa v0, v1, sext(v0) dst_sel:DWORD dst_unused:UNUSED_PAD src0_sel:DWORD src1_sel:WORD_0
	v_add_lshl_u32 v1, v5, v2, 12
	s_ashr_i32 s3, s16, 8
	global_load_lds_dwordx4 v144, s[14:15]
	s_add_i32 m0, s45, 0x12000
	v_lshl_add_u32 v146, v0, 1, v1
	s_add_u32 s4, s14, 0x80000
	global_load_lds_dwordx4 v146, s[14:15]
	s_addc_u32 s5, s15, 0
	s_add_i32 m0, s45, 0x14000
	s_add_i32 s48, s45, 0x2000
	global_load_lds_dwordx4 v144, s[4:5]
	s_add_i32 m0, s45, 0x16000
	v_mov_b32_e32 v145, 0
	global_load_lds_dwordx4 v146, s[4:5]
	s_mov_b32 m0, s45
	s_add_u32 s4, s12, 0x80000
	global_load_lds_dwordx4 v144, s[12:13]
	s_mov_b32 m0, s48
	s_addc_u32 s5, s13, 0
	s_add_i32 s49, s45, 0x4000
	global_load_lds_dwordx4 v146, s[12:13]
	s_mov_b32 m0, s49
	s_add_i32 s50, s45, 0x6000
	global_load_lds_dwordx4 v144, s[4:5]
	s_mov_b32 m0, s50
	v_mov_b32_e32 v147, v145
	global_load_lds_dwordx4 v146, s[4:5]
	s_cmp_eq_u32 s3, 1
	s_mov_b32 s17, 0
	v_lshl_add_u64 v[6:7], s[14:15], 0, v[144:145]
	v_lshl_add_u64 v[4:5], s[14:15], 0, v[146:147]
	v_lshl_add_u64 v[0:1], s[12:13], 0, v[144:145]
	s_cselect_b64 s[18:19], -1, 0
	s_cmp_lg_u32 s3, 1
	v_lshl_add_u64 v[2:3], s[12:13], 0, v[146:147]
	s_cbranch_scc1 .LBB0_846
	s_barrier
;     __device__ bool next(int i, Unit& u) const { const int L = i * G + c; if (L < 1536) return P.next(i, u); if (L < 1584) { u.pm = 32; u.pn = L - 1536; return true; } return false; }
;     __device__ bool next(int i, Unit& u) const { const int L = i * G + c; if (L < 256) return P.next(i, u); if (L < 264) { u.pm = 32; u.pn = L - 256; return true; } return false; }
; #define PG8_STAGE(bufoff, gbase, voff) do { _Pragma("unroll") for (int _i = 0; _i < 2; ++_i) \
;         __builtin_amdgcn_global_load_lds((const unsigned*)((const char*)(gbase) + (voff)[_i]), (LAS unsigned*)(lds + (bufoff) + ldsw + _i * 8192), 16, 0, 0); } while (0)
; #define PG8_WAIT_V(n) asm volatile("s_waitcnt vmcnt(" #n ")" ::: "memory")
; #define PG8_BAR __builtin_amdgcn_s_barrier()
; template <class Epi, class Sched, bool ALIGN_EPI = true>
; __device__ __forceinline__ void gemm_phase(LAS unsigned char* lds, const Gemm g, const Sched& S, const Epi& E) {
;     ...
;     PG8_STAGE(PG8_SB(1, 0), cB + kstep, voffB); PG8_STAGE(PG8_SA(1, 0), cA + kstep, voffA); PG8_STAGE(PG8_SB(1, 1), cB + hstep + kstep, voffB);
;     PG8_WAIT_V(6); PG8_BAR;
;     for (;;) {
;         const bool has_next = S.next(ui + 1, nxt);
;         const char* nA = has_next ? (const char*)g.A + (size_t)nxt.pm * tstep : cA; const char* nB = has_next ? (const char*)g.Bt + (size_t)nxt.pn * tstep : cB;
;     ...
;         for (int a = 0; a < 2; ++a)
; #pragma unroll
;             for (int b = 0; b < 2; ++b)
; #pragma unroll
;                 for (int m = 0; m < 4; ++m)
; #pragma unroll
;                     for (int n = 0; n < 2; ++n) acc[a][b][m][n] = (f32x4){0.f, 0.f, 0.f, 0.f};
;         cur = nxt; cA = nA; cB = nB; ++ui;
.LBB0_846:
	s_waitcnt vmcnt(0)
	v_bfe_u32 v10, v8, 4, 2
	s_add_u32 s51, s86, 0xe000
	v_and_b32_e32 v9, 15, v8
	v_lshlrev_b32_e32 v11, 4, v10
	v_lshlrev_b32_e32 v8, 2, v8
	s_mov_b64 s[20:21], 0x80
	s_addc_u32 s52, s87, 0
	s_and_b32 s53, s2, 3
	v_lshl_or_b32 v180, s3, 6, v9
	v_lshl_or_b32 v9, v9, 6, v11
	s_lshl_b32 s2, s3, 13
	v_and_b32_e32 v8, 32, v8
	s_add_i32 m0, s45, 0x18000
	v_lshl_add_u64 v[6:7], v[6:7], 0, s[20:21]
	v_bitop3_b32 v11, v9, s2, v8 bitop3:0xde
	s_lshl_b32 s2, s53, 12
	s_waitcnt vmcnt(2)
	s_barrier
	global_load_lds_dwordx4 v[6:7], off
	v_lshl_add_u64 v[4:5], v[4:5], 0, s[20:21]
	s_add_i32 m0, s45, 0x1a000
	s_add_i32 s54, s45, 0x8000
	s_add_i32 s55, s45, 0xa000
	v_bitop3_b32 v181, v9, s2, v8 bitop3:0xde
	global_load_lds_dwordx4 v[4:5], off
	v_lshl_add_u64 v[0:1], v[0:1], 0, s[20:21]
	s_mov_b32 m0, s54
	s_add_u32 s2, s14, 0x80080
	global_load_lds_dwordx4 v[0:1], off
	v_lshl_add_u64 v[0:1], v[2:3], 0, s[20:21]
	s_mov_b32 m0, s55
	s_addc_u32 s3, s15, 0
	global_load_lds_dwordx4 v[0:1], off
	s_add_i32 m0, s45, 0x1c000
	v_lshl_add_u64 v[0:1], s[2:3], 0, v[144:145]
	global_load_lds_dwordx4 v[0:1], off
	v_lshl_add_u64 v[0:1], s[2:3], 0, v[146:147]
	s_add_i32 m0, s45, 0x1e000
	s_cmpk_lt_u32 s16, 0x100
	global_load_lds_dwordx4 v[0:1], off
	s_cselect_b64 s[22:23], -1, 0
	s_lshr_b32 s2, s94, 3
	s_lshl_b32 s3, s94, 5
	s_and_b32 s2, s2, 24
	s_and_b32 s3, s3, 32
	s_or_b32 s2, s3, s2
	s_lshr_b32 s57, s2, 3
	s_ashr_i32 s2, s94, 31
	s_lshl_b32 s16, s94, 2
	s_lshr_b32 s2, s2, 29
	s_and_b32 s16, s16, 24
	s_bfe_u32 s3, s94, 0x30003
	s_add_i32 s2, s94, s2
	s_or_b32 s56, s16, s3
	s_ashr_i32 s3, s2, 3
	s_and_b32 s2, s2, -8
	s_sub_i32 s2, s94, s2
	s_lshl_b32 s16, s2, 5
	s_cmp_lt_i32 s2, 0
	s_mul_i32 s2, s2, 33
	s_cselect_b32 s2, s2, s16
	s_add_i32 s2, s2, s3
	s_ashr_i32 s3, s2, 31
	s_lshr_b32 s3, s3, 26
	s_add_i32 s3, s2, s3
	s_ashr_i32 s16, s3, 6
	s_andn2_b32 s3, s3, 63
	s_sub_i32 s2, s2, s3
	s_bfe_i32 s3, s2, 0x80000
	s_bfe_u32 s3, s3, 0x3000c
	s_add_i32 s3, s2, s3
	s_lshl_b32 s33, s16, 3
	s_bfe_i32 s16, s3, 0x80000
	s_and_b32 s3, s3, 0xf8
	s_waitcnt vmcnt(6)
	v_lshlrev_b32_e32 v0, 2, v10
	s_sub_i32 s2, s2, s3
	v_lshl_or_b32 v182, s53, 5, v0
	v_lshlrev_b32_e32 v0, 5, v10
	v_mov_b32_e32 v1, v145
	s_sext_i32_i16 s16, s16
	s_sext_i32_i8 s2, s2
	v_readlane_b32 s80, v234, 22
	v_readlane_b32 s82, v234, 31
	v_cmp_eq_u32_e64 s[4:5], 0, v10
	v_lshl_add_u64 v[148:149], s[0:1], 0, v[0:1]
	s_add_i32 s33, s33, s2
	s_ashr_i32 s58, s16, 3
	s_add_i32 s59, 0, 0x10000
	s_add_i32 s60, 0, 0x14000
	v_add_u32_e32 v183, 0, v11
	v_mov_b32_e32 v184, 0x358637bd
	s_mov_b32 s61, 0
	v_mov_b32_e32 v8, v208
	v_mov_b32_e32 v9, v209
	v_mov_b32_e32 v10, v210
	v_mov_b32_e32 v11, v211
	v_mov_b32_e32 v4, v212
	v_mov_b32_e32 v5, v213
	v_mov_b32_e32 v6, v214
	v_mov_b32_e32 v7, v215
	v_mov_b32_e32 v0, v216
	v_mov_b32_e32 v1, v217
	v_mov_b32_e32 v2, v218
	v_mov_b32_e32 v3, v219
	v_readlane_b32 s81, v234, 23
	v_readlane_b32 s83, v234, 32
	s_barrier
	s_branch .LBB0_849
.LBB0_847:
	s_mov_b32 s10, s26
	s_mov_b32 s44, s24
	s_mov_b64 s[14:15], s[30:31]
	s_mov_b64 s[12:13], s[28:29]
	s_mov_b32 s61, s62
	v_lshl_add_u32 v220, s44, 8, v180
	v_mov_b32_e32 v221, 0
	v_lshl_or_b32 v222, s10, 8, v182
	v_mov_b32_e32 v223, 0
	v_lshlrev_b64 v[220:221], 13, v[220:221]
	v_lshl_add_u64 v[220:221], s[84:85], 0, v[220:221]
	v_lshl_add_u64 v[220:221], v[222:223], 2, v[220:221]
	global_load_dwordx4 v[124:127], v[220:221], off
	global_load_dwordx4 v[120:123], v[220:221], off offset:64
	global_load_dwordx4 v[92:95], v[220:221], off offset:512
	global_load_dwordx4 v[88:91], v[220:221], off offset:576
	s_mov_b64 s[88:89], 0x20000
	v_lshl_add_u64 v[226:227], v[220:221], 0, s[88:89]
	global_load_dwordx4 v[116:119], v[226:227], off
	global_load_dwordx4 v[112:115], v[226:227], off offset:64
	global_load_dwordx4 v[84:87], v[226:227], off offset:512
	global_load_dwordx4 v[80:83], v[226:227], off offset:576
	s_mov_b64 s[88:89], 0x40000
	v_lshl_add_u64 v[224:225], v[220:221], 0, s[88:89]
	global_load_dwordx4 v[108:111], v[224:225], off
	global_load_dwordx4 v[104:107], v[224:225], off offset:64
	global_load_dwordx4 v[76:79], v[224:225], off offset:512
	global_load_dwordx4 v[72:75], v[224:225], off offset:576
	s_mov_b64 s[88:89], 0x60000
	v_lshl_add_u64 v[226:227], v[220:221], 0, s[88:89]
	global_load_dwordx4 v[100:103], v[226:227], off
	global_load_dwordx4 v[96:99], v[226:227], off offset:64
	global_load_dwordx4 v[68:71], v[226:227], off offset:512
	global_load_dwordx4 v[64:67], v[226:227], off offset:576
	s_mov_b64 s[88:89], 0x100000
	v_lshl_add_u64 v[224:225], v[220:221], 0, s[88:89]
	global_load_dwordx4 v[60:63], v[224:225], off
	global_load_dwordx4 v[56:59], v[224:225], off offset:64
	global_load_dwordx4 v[28:31], v[224:225], off offset:512
	global_load_dwordx4 v[24:27], v[224:225], off offset:576
	s_mov_b64 s[88:89], 0x120000
	v_lshl_add_u64 v[226:227], v[220:221], 0, s[88:89]
	global_load_dwordx4 v[52:55], v[226:227], off
	global_load_dwordx4 v[48:51], v[226:227], off offset:64
	global_load_dwordx4 v[20:23], v[226:227], off offset:512
	global_load_dwordx4 v[16:19], v[226:227], off offset:576
	s_mov_b64 s[88:89], 0x140000
	v_lshl_add_u64 v[224:225], v[220:221], 0, s[88:89]
	global_load_dwordx4 v[44:47], v[224:225], off
	global_load_dwordx4 v[40:43], v[224:225], off offset:64
	global_load_dwordx4 v[12:15], v[224:225], off offset:512
	global_load_dwordx4 v[8:11], v[224:225], off offset:576
	s_mov_b64 s[88:89], 0x160000
	v_lshl_add_u64 v[226:227], v[220:221], 0, s[88:89]
	global_load_dwordx4 v[36:39], v[226:227], off
	global_load_dwordx4 v[32:35], v[226:227], off offset:64
	global_load_dwordx4 v[4:7], v[226:227], off offset:512
	global_load_dwordx4 v[0:3], v[226:227], off offset:576
	s_waitcnt vmcnt(0)

; __device__ __forceinline__ void st_wt4(void* ptr, unsigned v) { asm volatile("global_store_dword %0, %1, off sc1" :: "v"(ptr), "v"(v) : "memory"); }
;     __device__ __forceinline__ void operator()(f32x4 (&acc)[2][2][4][2], const pg8::Unit& u, int wr, int wc, int fr, int fq) const {
;         const int row0 = u.pm * 256 + wr * 64 + fr, col0 = u.pn * 256 + wc * 32 + 4 * fq;
; #pragma unroll
;         for (int ai = 0; ai < 2; ++ai)
; #pragma unroll
;             for (int m = 0; m < 4; ++m) {
;                 const int row = row0 + ai * 128 + m * 16;
;                 const float* xr = oy + (size_t)row * DM + col0;
;                 float q = 0.f;
; #pragma unroll
;                 for (int bj = 0; bj < 2; ++bj)
; #pragma unroll
;                     for (int n = 0; n < 2; ++n) {
;                         const f32x4 o = *(const f32x4*)(xr + bj * 128 + n * 16) + acc[ai][bj][m][n];
;                         acc[ai][bj][m][n] = o;
;                         q += (o[0] * o[0] + o[1] * o[1]) + (o[2] * o[2] + o[3] * o[3]);
;                     }
;                 q += __shfl_xor(q, 16); q += __shfl_xor(q, 32);
;                 if (fq == 0) st_wt4(ss + (size_t)row * 32 + u.pn * 4 + wc, __float_as_uint(q));
;             }
.LBB0_875:
	v_lshl_add_u32 v132, s44, 8, v180
	v_ashrrev_i32_e32 v133, 31, v132
	v_lshl_or_b32 v128, s10, 8, v182
	v_lshlrev_b64 v[130:131], 13, v[132:133]
	v_ashrrev_i32_e32 v129, 31, v128
	v_lshl_add_u64 v[130:131], s[84:85], 0, v[130:131]
	v_lshl_add_u64 v[150:151], v[128:129], 2, v[130:131]
	v_and_b32_e32 v131, 64, v195
	v_xor_b32_e32 v130, 16, v195
	v_add_u32_e32 v131, 64, v131
	v_cmp_lt_i32_e32 vcc, v130, v131
	s_lshl_b32 s36, s10, 2
	s_ashr_i32 s37, s36, 31
	v_cndmask_b32_e32 v130, v195, v130, vcc
	v_lshlrev_b32_e32 v185, 2, v130
	v_mul_f32_e32 v130, v125, v125
	v_mul_f32_e32 v134, v127, v127
	v_mul_f32_e32 v135, v121, v121
	v_mul_f32_e32 v136, v123, v123
	v_mul_f32_e32 v137, v93, v93
	v_mul_f32_e32 v138, v95, v95
	v_fmac_f32_e32 v130, v124, v124
	v_fmac_f32_e32 v134, v126, v126
	v_fmac_f32_e32 v135, v120, v120
	v_fmac_f32_e32 v136, v122, v122
	v_mul_f32_e32 v139, v89, v89
	v_mul_f32_e32 v140, v91, v91
	v_fmac_f32_e32 v137, v92, v92
	v_fmac_f32_e32 v138, v94, v94
	v_add_f32_e32 v130, v130, v134
	v_add_f32_e32 v134, v135, v136
	v_fmac_f32_e32 v139, v88, v88
	v_fmac_f32_e32 v140, v90, v90
	v_add_f32_e32 v135, v137, v138
	v_add_f32_e32 v130, v130, v134
	v_add_f32_e32 v130, v130, v135
	v_add_f32_e32 v134, v139, v140
	v_add_f32_e32 v130, v130, v134
	ds_bpermute_b32 v134, v185, v130
	v_xor_b32_e32 v135, 32, v195
	v_cmp_lt_i32_e32 vcc, v135, v131
	s_waitcnt lgkmcnt(0)
	v_add_f32_e32 v134, v130, v134
	v_cndmask_b32_e32 v131, v195, v135, vcc
	v_lshlrev_b32_e32 v186, 2, v131
	ds_bpermute_b32 v135, v186, v134
	v_lshlrev_b64 v[130:131], 7, v[132:133]
	s_and_saveexec_b64 s[38:39], s[4:5]
	s_cbranch_execz .LBB0_877
	s_waitcnt lgkmcnt(0)
	v_add_f32_e32 v133, v134, v135
	v_lshl_add_u64 v[134:135], s[0:1], 0, v[130:131]
	v_lshl_add_u64 v[134:135], s[36:37], 2, v[134:135]
	s_lshl_b32 s16, s53, 2
	v_lshl_add_u64 v[134:135], v[134:135], 0, s[16:17]
	global_store_dword v[134:135], v133, off sc1
.LBB0_877:
	s_or_b64 exec, exec, s[38:39]
	v_or_b32_e32 v142, 16, v132
	v_ashrrev_i32_e32 v143, 31, v142
	s_waitcnt lgkmcnt(0)
	v_lshlrev_b64 v[134:135], 13, v[142:143]
	v_lshl_add_u64 v[134:135], s[84:85], 0, v[134:135]
	v_lshl_add_u64 v[152:153], v[128:129], 2, v[134:135]
	v_lshlrev_b64 v[166:167], 7, v[142:143]
	v_mul_f32_e32 v133, v117, v117
	v_mul_f32_e32 v134, v119, v119
	v_mul_f32_e32 v135, v113, v113
	v_mul_f32_e32 v136, v115, v115
	v_mul_f32_e32 v137, v85, v85
	v_mul_f32_e32 v138, v87, v87
	v_fmac_f32_e32 v133, v116, v116
	v_fmac_f32_e32 v134, v118, v118
	v_fmac_f32_e32 v135, v112, v112
	v_fmac_f32_e32 v136, v114, v114
	v_mul_f32_e32 v139, v81, v81
	v_mul_f32_e32 v140, v83, v83
	v_fmac_f32_e32 v137, v84, v84
	v_fmac_f32_e32 v138, v86, v86
	v_add_f32_e32 v133, v133, v134
	v_add_f32_e32 v134, v135, v136
	v_fmac_f32_e32 v139, v80, v80
	v_fmac_f32_e32 v140, v82, v82
	v_add_f32_e32 v135, v137, v138
	v_add_f32_e32 v133, v133, v134
	v_add_f32_e32 v133, v133, v135
	v_add_f32_e32 v134, v139, v140
	v_add_f32_e32 v133, v133, v134
	ds_bpermute_b32 v134, v185, v133
	s_waitcnt lgkmcnt(0)
	v_add_f32_e32 v133, v133, v134
	ds_bpermute_b32 v134, v186, v133
	s_and_saveexec_b64 s[38:39], s[4:5]
	s_cbranch_execz .LBB0_879
	s_waitcnt lgkmcnt(0)
	v_add_f32_e32 v133, v133, v134
	v_lshl_add_u64 v[134:135], s[0:1], 0, v[166:167]
	v_lshl_add_u64 v[134:135], s[36:37], 2, v[134:135]
	s_lshl_b32 s16, s53, 2
	v_lshl_add_u64 v[134:135], v[134:135], 0, s[16:17]
	global_store_dword v[134:135], v133, off sc1
.LBB0_879:
	s_or_b64 exec, exec, s[38:39]
	v_or_b32_e32 v142, 32, v132
	v_ashrrev_i32_e32 v143, 31, v142
	s_waitcnt lgkmcnt(0)
	v_lshlrev_b64 v[134:135], 13, v[142:143]
	v_lshl_add_u64 v[134:135], s[84:85], 0, v[134:135]
	v_lshl_add_u64 v[154:155], v[128:129], 2, v[134:135]
	v_lshlrev_b64 v[168:169], 7, v[142:143]
	v_mul_f32_e32 v133, v109, v109
	v_mul_f32_e32 v134, v111, v111
	v_mul_f32_e32 v135, v105, v105
	v_mul_f32_e32 v136, v107, v107
	v_mul_f32_e32 v137, v77, v77
	v_mul_f32_e32 v138, v79, v79
	v_fmac_f32_e32 v133, v108, v108
	v_fmac_f32_e32 v134, v110, v110
	v_fmac_f32_e32 v135, v104, v104
	v_fmac_f32_e32 v136, v106, v106
	v_mul_f32_e32 v139, v73, v73
	v_mul_f32_e32 v140, v75, v75
	v_fmac_f32_e32 v137, v76, v76
	v_fmac_f32_e32 v138, v78, v78
	v_add_f32_e32 v133, v133, v134
	v_add_f32_e32 v134, v135, v136
	v_fmac_f32_e32 v139, v72, v72
	v_fmac_f32_e32 v140, v74, v74
	v_add_f32_e32 v135, v137, v138
	v_add_f32_e32 v133, v133, v134
	v_add_f32_e32 v133, v133, v135
	v_add_f32_e32 v134, v139, v140
	v_add_f32_e32 v133, v133, v134
	ds_bpermute_b32 v134, v185, v133
	s_waitcnt lgkmcnt(0)
	v_add_f32_e32 v133, v133, v134
	ds_bpermute_b32 v134, v186, v133
	s_and_saveexec_b64 s[38:39], s[4:5]
	s_cbranch_execz .LBB0_881
	s_waitcnt lgkmcnt(0)
	v_add_f32_e32 v133, v133, v134
	v_lshl_add_u64 v[134:135], s[0:1], 0, v[168:169]
	v_lshl_add_u64 v[134:135], s[36:37], 2, v[134:135]
	s_lshl_b32 s16, s53, 2
	v_lshl_add_u64 v[134:135], v[134:135], 0, s[16:17]
	global_store_dword v[134:135], v133, off sc1
; __device__ __forceinline__ void st_wt4(void* ptr, unsigned v) { asm volatile("global_store_dword %0, %1, off sc1" :: "v"(ptr), "v"(v) : "memory"); }
;     __device__ __forceinline__ void operator()(f32x4 (&acc)[2][2][4][2], const pg8::Unit& u, int wr, int wc, int fr, int fq) const {
;     ...
;         for (int ai = 0; ai < 2; ++ai)
; #pragma unroll
;             for (int m = 0; m < 4; ++m) {
;                 const int row = row0 + ai * 128 + m * 16;
;                 const float* xr = oy + (size_t)row * DM + col0;
;                 float q = 0.f;
; #pragma unroll
;                 for (int bj = 0; bj < 2; ++bj)
; #pragma unroll
;                     for (int n = 0; n < 2; ++n) {
;                         const f32x4 o = *(const f32x4*)(xr + bj * 128 + n * 16) + acc[ai][bj][m][n];
;                         acc[ai][bj][m][n] = o;
;                         q += (o[0] * o[0] + o[1] * o[1]) + (o[2] * o[2] + o[3] * o[3]);
;                     }
;                 q += __shfl_xor(q, 16); q += __shfl_xor(q, 32);
;                 if (fq == 0) st_wt4(ss + (size_t)row * 32 + u.pn * 4 + wc, __float_as_uint(q));
;             }
.LBB0_881:
	s_or_b64 exec, exec, s[38:39]
	v_or_b32_e32 v142, 48, v132
	v_ashrrev_i32_e32 v143, 31, v142
	s_waitcnt lgkmcnt(0)
	v_lshlrev_b64 v[134:135], 13, v[142:143]
	v_lshl_add_u64 v[134:135], s[84:85], 0, v[134:135]
	v_lshl_add_u64 v[156:157], v[128:129], 2, v[134:135]
	v_lshlrev_b64 v[170:171], 7, v[142:143]
	v_mul_f32_e32 v133, v101, v101
	v_mul_f32_e32 v134, v103, v103
	v_mul_f32_e32 v135, v97, v97
	v_mul_f32_e32 v136, v99, v99
	v_mul_f32_e32 v137, v69, v69
	v_mul_f32_e32 v138, v71, v71
	v_fmac_f32_e32 v133, v100, v100
	v_fmac_f32_e32 v134, v102, v102
	v_fmac_f32_e32 v135, v96, v96
	v_fmac_f32_e32 v136, v98, v98
	v_mul_f32_e32 v139, v65, v65
	v_mul_f32_e32 v140, v67, v67
	v_fmac_f32_e32 v137, v68, v68
	v_fmac_f32_e32 v138, v70, v70
	v_add_f32_e32 v133, v133, v134
	v_add_f32_e32 v134, v135, v136
	v_fmac_f32_e32 v139, v64, v64
	v_fmac_f32_e32 v140, v66, v66
	v_add_f32_e32 v135, v137, v138
	v_add_f32_e32 v133, v133, v134
	v_add_f32_e32 v133, v133, v135
	v_add_f32_e32 v134, v139, v140
	v_add_f32_e32 v133, v133, v134
	ds_bpermute_b32 v134, v185, v133
	s_waitcnt lgkmcnt(0)
	v_add_f32_e32 v133, v133, v134
	ds_bpermute_b32 v134, v186, v133
	s_and_saveexec_b64 s[38:39], s[4:5]
	s_cbranch_execz .LBB0_883
	s_waitcnt lgkmcnt(0)
	v_add_f32_e32 v133, v133, v134
	v_lshl_add_u64 v[134:135], s[0:1], 0, v[170:171]
	v_lshl_add_u64 v[134:135], s[36:37], 2, v[134:135]
	s_lshl_b32 s16, s53, 2
	v_lshl_add_u64 v[134:135], v[134:135], 0, s[16:17]
	global_store_dword v[134:135], v133, off sc1
.LBB0_883:
	s_or_b64 exec, exec, s[38:39]
	v_add_u32_e32 v142, 0x80, v132
	v_ashrrev_i32_e32 v143, 31, v142
	s_waitcnt lgkmcnt(0)
	v_lshlrev_b64 v[134:135], 13, v[142:143]
	v_lshl_add_u64 v[134:135], s[84:85], 0, v[134:135]
	v_lshl_add_u64 v[158:159], v[128:129], 2, v[134:135]
	v_mul_f32_e32 v133, v61, v61
	v_mul_f32_e32 v134, v63, v63
	v_mul_f32_e32 v135, v57, v57
	v_mul_f32_e32 v136, v59, v59
	v_mul_f32_e32 v137, v29, v29
	v_mul_f32_e32 v138, v31, v31
	v_fmac_f32_e32 v133, v60, v60
	v_fmac_f32_e32 v134, v62, v62
	v_fmac_f32_e32 v135, v56, v56
	v_fmac_f32_e32 v136, v58, v58
	v_mul_f32_e32 v139, v25, v25
	v_mul_f32_e32 v140, v27, v27
	v_fmac_f32_e32 v137, v28, v28
	v_fmac_f32_e32 v138, v30, v30
	v_add_f32_e32 v133, v133, v134
	v_add_f32_e32 v134, v135, v136
	v_fmac_f32_e32 v139, v24, v24
	v_fmac_f32_e32 v140, v26, v26
	v_add_f32_e32 v135, v137, v138
	v_add_f32_e32 v133, v133, v134
	v_add_f32_e32 v133, v133, v135
	v_add_f32_e32 v134, v139, v140
	v_add_f32_e32 v133, v133, v134
	ds_bpermute_b32 v134, v185, v133
	v_lshlrev_b64 v[172:173], 7, v[142:143]
	s_waitcnt lgkmcnt(0)
	v_add_f32_e32 v133, v133, v134
	ds_bpermute_b32 v134, v186, v133
	s_and_saveexec_b64 s[38:39], s[4:5]
	s_cbranch_execz .LBB0_885
	s_waitcnt lgkmcnt(0)
	v_add_f32_e32 v133, v133, v134
	v_lshl_add_u64 v[134:135], s[0:1], 0, v[172:173]
	v_lshl_add_u64 v[134:135], s[36:37], 2, v[134:135]
	s_lshl_b32 s16, s53, 2
	v_lshl_add_u64 v[134:135], v[134:135], 0, s[16:17]
	global_store_dword v[134:135], v133, off sc1
; __device__ __forceinline__ void st_wt4(void* ptr, unsigned v) { asm volatile("global_store_dword %0, %1, off sc1" :: "v"(ptr), "v"(v) : "memory"); }
;     __device__ __forceinline__ void operator()(f32x4 (&acc)[2][2][4][2], const pg8::Unit& u, int wr, int wc, int fr, int fq) const {
;     ...
;         for (int ai = 0; ai < 2; ++ai)
; #pragma unroll
;             for (int m = 0; m < 4; ++m) {
;                 const int row = row0 + ai * 128 + m * 16;
;                 const float* xr = oy + (size_t)row * DM + col0;
;                 float q = 0.f;
; #pragma unroll
;                 for (int bj = 0; bj < 2; ++bj)
; #pragma unroll
;                     for (int n = 0; n < 2; ++n) {
;                         const f32x4 o = *(const f32x4*)(xr + bj * 128 + n * 16) + acc[ai][bj][m][n];
;                         acc[ai][bj][m][n] = o;
;                         q += (o[0] * o[0] + o[1] * o[1]) + (o[2] * o[2] + o[3] * o[3]);
;                     }
;                 q += __shfl_xor(q, 16); q += __shfl_xor(q, 32);
;                 if (fq == 0) st_wt4(ss + (size_t)row * 32 + u.pn * 4 + wc, __float_as_uint(q));
;             }
.LBB0_885:
	s_or_b64 exec, exec, s[38:39]
	v_add_u32_e32 v142, 0x90, v132
	v_ashrrev_i32_e32 v143, 31, v142
	s_waitcnt lgkmcnt(0)
	v_lshlrev_b64 v[134:135], 13, v[142:143]
	v_lshl_add_u64 v[134:135], s[84:85], 0, v[134:135]
	v_lshl_add_u64 v[160:161], v[128:129], 2, v[134:135]
	v_mul_f32_e32 v133, v53, v53
	v_mul_f32_e32 v134, v55, v55
	v_mul_f32_e32 v135, v49, v49
	v_mul_f32_e32 v136, v51, v51
	v_mul_f32_e32 v137, v21, v21
	v_mul_f32_e32 v138, v23, v23
	v_fmac_f32_e32 v133, v52, v52
	v_fmac_f32_e32 v134, v54, v54
	v_fmac_f32_e32 v135, v48, v48
	v_fmac_f32_e32 v136, v50, v50
	v_mul_f32_e32 v139, v17, v17
	v_mul_f32_e32 v140, v19, v19
	v_fmac_f32_e32 v137, v20, v20
	v_fmac_f32_e32 v138, v22, v22
	v_add_f32_e32 v133, v133, v134
	v_add_f32_e32 v134, v135, v136
	v_fmac_f32_e32 v139, v16, v16
	v_fmac_f32_e32 v140, v18, v18
	v_add_f32_e32 v135, v137, v138
	v_add_f32_e32 v133, v133, v134
	v_add_f32_e32 v133, v133, v135
	v_add_f32_e32 v134, v139, v140
	v_add_f32_e32 v133, v133, v134
	ds_bpermute_b32 v134, v185, v133
	v_lshlrev_b64 v[174:175], 7, v[142:143]
	s_waitcnt lgkmcnt(0)
	v_add_f32_e32 v133, v133, v134
	ds_bpermute_b32 v134, v186, v133
	s_and_saveexec_b64 s[38:39], s[4:5]
	s_cbranch_execz .LBB0_887
	s_waitcnt lgkmcnt(0)
	v_add_f32_e32 v133, v133, v134
	v_lshl_add_u64 v[134:135], s[0:1], 0, v[174:175]
	v_lshl_add_u64 v[134:135], s[36:37], 2, v[134:135]
	s_lshl_b32 s16, s53, 2
	v_lshl_add_u64 v[134:135], v[134:135], 0, s[16:17]
	global_store_dword v[134:135], v133, off sc1
.LBB0_887:
	s_or_b64 exec, exec, s[38:39]
	v_add_u32_e32 v142, 0xa0, v132
	v_ashrrev_i32_e32 v143, 31, v142
	s_waitcnt lgkmcnt(0)
	v_lshlrev_b64 v[134:135], 13, v[142:143]
	v_lshl_add_u64 v[134:135], s[84:85], 0, v[134:135]
	v_lshl_add_u64 v[162:163], v[128:129], 2, v[134:135]
	v_mul_f32_e32 v133, v45, v45
	v_mul_f32_e32 v134, v47, v47
	v_mul_f32_e32 v135, v41, v41
	v_mul_f32_e32 v136, v43, v43
	v_mul_f32_e32 v137, v13, v13
	v_mul_f32_e32 v138, v15, v15
	v_fmac_f32_e32 v133, v44, v44
	v_fmac_f32_e32 v134, v46, v46
	v_fmac_f32_e32 v135, v40, v40
	v_fmac_f32_e32 v136, v42, v42
	v_mul_f32_e32 v139, v9, v9
	v_mul_f32_e32 v140, v11, v11
	v_fmac_f32_e32 v137, v12, v12
	v_fmac_f32_e32 v138, v14, v14
	v_add_f32_e32 v133, v133, v134
	v_add_f32_e32 v134, v135, v136
	v_fmac_f32_e32 v139, v8, v8
	v_fmac_f32_e32 v140, v10, v10
	v_add_f32_e32 v135, v137, v138
	v_add_f32_e32 v133, v133, v134
	v_add_f32_e32 v133, v133, v135
	v_add_f32_e32 v134, v139, v140
	v_add_f32_e32 v133, v133, v134
	ds_bpermute_b32 v134, v185, v133
	v_lshlrev_b64 v[176:177], 7, v[142:143]
	s_waitcnt lgkmcnt(0)
	v_add_f32_e32 v133, v133, v134
	ds_bpermute_b32 v134, v186, v133
	s_and_saveexec_b64 s[38:39], s[4:5]
	s_cbranch_execz .LBB0_889
	s_waitcnt lgkmcnt(0)
	v_add_f32_e32 v133, v133, v134
	v_lshl_add_u64 v[134:135], s[0:1], 0, v[176:177]
	v_lshl_add_u64 v[134:135], s[36:37], 2, v[134:135]
	s_lshl_b32 s16, s53, 2
	v_lshl_add_u64 v[134:135], v[134:135], 0, s[16:17]
	global_store_dword v[134:135], v133, off sc1
.LBB0_889:
	s_or_b64 exec, exec, s[38:39]
	v_add_u32_e32 v178, 0xb0, v132
	v_ashrrev_i32_e32 v179, 31, v178
	v_lshlrev_b64 v[132:133], 13, v[178:179]
	v_lshl_add_u64 v[132:133], s[84:85], 0, v[132:133]
	v_lshl_add_u64 v[164:165], v[128:129], 2, v[132:133]
	s_waitcnt lgkmcnt(0)
	v_lshlrev_b64 v[178:179], 7, v[178:179]
	v_mul_f32_e32 v132, v37, v37
	v_mul_f32_e32 v133, v39, v39
	v_mul_f32_e32 v134, v33, v33
	v_mul_f32_e32 v135, v35, v35
	v_mul_f32_e32 v136, v5, v5
	v_mul_f32_e32 v137, v7, v7
	v_fmac_f32_e32 v132, v36, v36
	v_fmac_f32_e32 v133, v38, v38
	v_fmac_f32_e32 v134, v32, v32
	v_fmac_f32_e32 v135, v34, v34
	v_mul_f32_e32 v138, v1, v1
	v_mul_f32_e32 v139, v3, v3
	v_fmac_f32_e32 v136, v4, v4
	v_fmac_f32_e32 v137, v6, v6
	v_add_f32_e32 v132, v132, v133
	v_add_f32_e32 v133, v134, v135
	v_fmac_f32_e32 v138, v0, v0
	v_fmac_f32_e32 v139, v2, v2
	v_add_f32_e32 v134, v136, v137
	v_add_f32_e32 v132, v132, v133
	v_add_f32_e32 v132, v132, v134
	v_add_f32_e32 v133, v138, v139
	v_add_f32_e32 v132, v132, v133
	ds_bpermute_b32 v133, v185, v132
	s_waitcnt lgkmcnt(0)
	v_add_f32_e32 v132, v132, v133
	ds_bpermute_b32 v133, v186, v132
	s_and_saveexec_b64 s[38:39], s[4:5]
	s_cbranch_execz .LBB0_891
	s_waitcnt lgkmcnt(0)
	v_add_f32_e32 v134, v132, v133
	v_lshl_add_u64 v[132:133], s[0:1], 0, v[178:179]
	v_lshl_add_u64 v[132:133], s[36:37], 2, v[132:133]
	s_lshl_b32 s16, s53, 2
	v_lshl_add_u64 v[132:133], v[132:133], 0, s[16:17]
	global_store_dword v[132:133], v134, off sc1

;     __device__ __forceinline__ void operator()(f32x4 (&acc)[2][2][4][2], const pg8::Unit& u, int wr, int wc, int fr, int fq) const {
;     ...
;         asm volatile("" ::: "memory"); __builtin_amdgcn_s_barrier(); asm volatile("" ::: "memory");
;         f32x4 gg[2][2];
; #pragma unroll
;         for (int bj = 0; bj < 2; ++bj)
; #pragma unroll
;             for (int n = 0; n < 2; ++n) gg[bj][n] = *(const f32x4*)(fng + col0 + bj * 128 + n * 16);
; #pragma unroll
;         for (int ai = 0; ai < 2; ++ai)
; #pragma unroll
;             for (int m = 0; m < 4; ++m) {
;                 const int row = row0 + ai * 128 + m * 16;
;                 const f32x4 pa = *(const f32x4*)(ss + (size_t)row * 32 + 8 * fq), pb = *(const f32x4*)(ss + (size_t)row * 32 + 8 * fq + 4);
;                 float sq = ((pa[0] + pa[1]) + (pa[2] + pa[3])) + ((pb[0] + pb[1]) + (pb[2] + pb[3]));
;                 sq += __shfl_xor(sq, 16); sq += __shfl_xor(sq, 32);
;                 const float rinv = __builtin_amdgcn_rsqf(sq * (1.0f / DM) + 1e-6f);
.LBB0_904:
	s_or_b64 exec, exec, s[36:37]
	s_barrier
	s_waitcnt lgkmcnt(0)
	v_lshl_add_u64 v[130:131], v[148:149], 0, v[130:131]
	v_lshl_add_u64 v[166:167], v[148:149], 0, v[166:167]
	v_lshl_add_u64 v[168:169], v[148:149], 0, v[168:169]
	v_lshl_add_u64 v[170:171], v[148:149], 0, v[170:171]
	v_lshl_add_u64 v[172:173], v[148:149], 0, v[172:173]
	v_lshl_add_u64 v[174:175], v[148:149], 0, v[174:175]
	v_lshl_add_u64 v[176:177], v[148:149], 0, v[176:177]
	v_lshl_add_u64 v[178:179], v[148:149], 0, v[178:179]
	v_readlane_b32 s64, v234, 3
	v_readlane_b32 s74, v234, 13
	v_readlane_b32 s75, v234, 14
	global_load_dwordx4 v[196:199], v[130:131], off
	global_load_dwordx4 v[200:203], v[130:131], off offset:16
	global_load_dwordx4 v[204:207], v[166:167], off
	global_load_dwordx4 v[208:211], v[166:167], off offset:16
	global_load_dwordx4 v[212:215], v[168:169], off
	global_load_dwordx4 v[216:219], v[168:169], off offset:16
	global_load_dwordx4 v[220:223], v[170:171], off
	global_load_dwordx4 v[224:227], v[170:171], off offset:16
	global_load_dwordx4 v[228:231], v[172:173], off
	global_load_dwordx4 v[236:239], v[172:173], off offset:16
	global_load_dwordx4 v[240:243], v[174:175], off
	global_load_dwordx4 v[244:247], v[174:175], off offset:16
	global_load_dwordx4 v[248:251], v[176:177], off
	global_load_dwordx4 v[188:191], v[176:177], off offset:16
	global_load_dwordx4 v[152:155], v[178:179], off
	global_load_dwordx4 v[156:159], v[178:179], off offset:16
	v_lshl_add_u64 v[128:129], v[128:129], 2, s[74:75]
	global_load_dwordx4 v[140:143], v[128:129], off
	global_load_dwordx4 v[136:139], v[128:129], off offset:64
	global_load_dwordx4 v[132:135], v[128:129], off offset:512
	s_nop 0
	global_load_dwordx4 v[128:131], v[128:129], off offset:576
	v_readlane_b32 s65, v234, 4
	v_readlane_b32 s66, v234, 5
	v_readlane_b32 s67, v234, 6
	v_readlane_b32 s68, v234, 7
	v_readlane_b32 s69, v234, 8
	v_readlane_b32 s70, v234, 9
	v_readlane_b32 s71, v234, 10
	v_readlane_b32 s72, v234, 11
	v_readlane_b32 s73, v234, 12
	v_readlane_b32 s76, v234, 15
	v_readlane_b32 s77, v234, 16
	v_readlane_b32 s78, v234, 17
	v_readlane_b32 s79, v234, 18
	s_waitcnt vmcnt(18)
	v_add_f32_e32 v196, v196, v197
	v_add_f32_e32 v198, v198, v199
	v_add_f32_e32 v200, v200, v201
	v_add_f32_e32 v202, v202, v203
	v_add_f32_e32 v196, v196, v198
	v_add_f32_e32 v200, v200, v202
	v_add_f32_e32 v196, v196, v200
	ds_bpermute_b32 v197, v185, v196
	s_waitcnt vmcnt(16)
	v_add_f32_e32 v204, v204, v205
	v_add_f32_e32 v206, v206, v207
	v_add_f32_e32 v208, v208, v209
	v_add_f32_e32 v210, v210, v211
	v_add_f32_e32 v204, v204, v206
	v_add_f32_e32 v208, v208, v210
	v_add_f32_e32 v204, v204, v208
	ds_bpermute_b32 v205, v185, v204
	s_waitcnt vmcnt(14)
	v_add_f32_e32 v212, v212, v213
	v_add_f32_e32 v214, v214, v215
	v_add_f32_e32 v216, v216, v217
	v_add_f32_e32 v218, v218, v219
	v_add_f32_e32 v212, v212, v214
	v_add_f32_e32 v216, v216, v218
	v_add_f32_e32 v212, v212, v216
	ds_bpermute_b32 v213, v185, v212
	s_waitcnt vmcnt(12)
	v_add_f32_e32 v220, v220, v221
	v_add_f32_e32 v222, v222, v223
	v_add_f32_e32 v224, v224, v225
	v_add_f32_e32 v226, v226, v227
	v_add_f32_e32 v220, v220, v222
	v_add_f32_e32 v224, v224, v226
	v_add_f32_e32 v220, v220, v224
	ds_bpermute_b32 v221, v185, v220
	s_waitcnt vmcnt(10)
	v_add_f32_e32 v228, v228, v229
	v_add_f32_e32 v230, v230, v231
	v_add_f32_e32 v236, v236, v237
	v_add_f32_e32 v238, v238, v239
	v_add_f32_e32 v228, v228, v230
	v_add_f32_e32 v236, v236, v238
	v_add_f32_e32 v228, v228, v236
	ds_bpermute_b32 v229, v185, v228
	s_waitcnt vmcnt(8)
	v_add_f32_e32 v240, v240, v241
	v_add_f32_e32 v242, v242, v243
	v_add_f32_e32 v244, v244, v245
	v_add_f32_e32 v246, v246, v247
	v_add_f32_e32 v240, v240, v242
	v_add_f32_e32 v244, v244, v246
	v_add_f32_e32 v240, v240, v244
	ds_bpermute_b32 v241, v185, v240
	s_waitcnt vmcnt(6)
	v_add_f32_e32 v248, v248, v249
	v_add_f32_e32 v250, v250, v251
	v_add_f32_e32 v188, v188, v189
	v_add_f32_e32 v190, v190, v191
	v_add_f32_e32 v248, v248, v250
	v_add_f32_e32 v188, v188, v190
	v_add_f32_e32 v248, v248, v188
	ds_bpermute_b32 v249, v185, v248
	s_waitcnt vmcnt(4)
	v_add_f32_e32 v152, v152, v153
	v_add_f32_e32 v154, v154, v155
	v_add_f32_e32 v156, v156, v157
	v_add_f32_e32 v158, v158, v159
	v_add_f32_e32 v152, v152, v154
	v_add_f32_e32 v156, v156, v158
	v_add_f32_e32 v152, v152, v156
	ds_bpermute_b32 v153, v185, v152
	s_waitcnt lgkmcnt(7)
	v_add_f32_e32 v196, v196, v197
	ds_bpermute_b32 v197, v186, v196
	s_waitcnt lgkmcnt(7)
	v_add_f32_e32 v204, v204, v205
	ds_bpermute_b32 v205, v186, v204
	s_waitcnt lgkmcnt(7)
	v_add_f32_e32 v212, v212, v213
	ds_bpermute_b32 v213, v186, v212
	s_waitcnt lgkmcnt(7)
	v_add_f32_e32 v220, v220, v221
	ds_bpermute_b32 v221, v186, v220
	s_waitcnt lgkmcnt(7)
	v_add_f32_e32 v228, v228, v229
	ds_bpermute_b32 v229, v186, v228
	s_waitcnt lgkmcnt(7)
	v_add_f32_e32 v240, v240, v241
	ds_bpermute_b32 v241, v186, v240
	s_waitcnt lgkmcnt(7)
	v_add_f32_e32 v248, v248, v249
	ds_bpermute_b32 v249, v186, v248
	s_waitcnt lgkmcnt(7)
	v_add_f32_e32 v152, v152, v153
	ds_bpermute_b32 v153, v186, v152
	s_waitcnt lgkmcnt(7)
	v_add_f32_e32 v196, v196, v197
	v_fmamk_f32 v196, v196, 0x3a000000, v184
	v_rsq_f32_e32 v196, v196
	s_waitcnt lgkmcnt(6)
	v_add_f32_e32 v204, v204, v205
	v_fmamk_f32 v204, v204, 0x3a000000, v184
	v_rsq_f32_e32 v204, v204
	s_waitcnt lgkmcnt(5)
	v_add_f32_e32 v212, v212, v213
	v_fmamk_f32 v212, v212, 0x3a000000, v184
	v_rsq_f32_e32 v212, v212
	s_waitcnt lgkmcnt(4)
	v_add_f32_e32 v220, v220, v221
	v_fmamk_f32 v220, v220, 0x3a000000, v184
	v_rsq_f32_e32 v220, v220
	s_waitcnt lgkmcnt(3)
	v_add_f32_e32 v228, v228, v229
	v_fmamk_f32 v228, v228, 0x3a000000, v184
	v_rsq_f32_e32 v228, v228
	s_waitcnt lgkmcnt(2)
;     __device__ __forceinline__ void operator()(f32x4 (&acc)[2][2][4][2], const pg8::Unit& u, int wr, int wc, int fr, int fq) const {
;     ...
; #pragma unroll
;         for (int ai = 0; ai < 2; ++ai)
; #pragma unroll
;             for (int m = 0; m < 4; ++m) {
;                 const int row = row0 + ai * 128 + m * 16;
;                 const f32x4 pa = *(const f32x4*)(ss + (size_t)row * 32 + 8 * fq), pb = *(const f32x4*)(ss + (size_t)row * 32 + 8 * fq + 4);
;                 float sq = ((pa[0] + pa[1]) + (pa[2] + pa[3])) + ((pb[0] + pb[1]) + (pb[2] + pb[3]));
;                 sq += __shfl_xor(sq, 16); sq += __shfl_xor(sq, 32);
;                 const float rinv = __builtin_amdgcn_rsqf(sq * (1.0f / DM) + 1e-6f);
;                 float* orow = oy + (size_t)row * DM + col0;
; #pragma unroll
;                 for (int bj = 0; bj < 2; ++bj)
; #pragma unroll
;                     for (int n = 0; n < 2; ++n) __builtin_nontemporal_store(acc[ai][bj][m][n] * rinv * gg[bj][n], (f32x4*)(orow + bj * 128 + n * 16));
;             }
	v_add_f32_e32 v240, v240, v241
	v_fmamk_f32 v240, v240, 0x3a000000, v184
	v_rsq_f32_e32 v240, v240
	s_waitcnt lgkmcnt(1)
	v_add_f32_e32 v248, v248, v249
	v_fmamk_f32 v248, v248, 0x3a000000, v184
	v_rsq_f32_e32 v248, v248
	s_waitcnt lgkmcnt(0)
	v_add_f32_e32 v152, v152, v153
	v_fmamk_f32 v152, v152, 0x3a000000, v184
	v_rsq_f32_e32 v152, v152
	s_nop 0
	s_waitcnt vmcnt(0)
	v_pk_mul_f32 v[124:125], v[124:125], v[196:197] op_sel_hi:[1,0]
	v_pk_mul_f32 v[126:127], v[126:127], v[196:197] op_sel_hi:[1,0]
	v_pk_mul_f32 v[120:121], v[120:121], v[196:197] op_sel_hi:[1,0]
	v_pk_mul_f32 v[122:123], v[122:123], v[196:197] op_sel_hi:[1,0]
	v_pk_mul_f32 v[92:93], v[92:93], v[196:197] op_sel_hi:[1,0]
	v_pk_mul_f32 v[94:95], v[94:95], v[196:197] op_sel_hi:[1,0]
	v_pk_mul_f32 v[88:89], v[88:89], v[196:197] op_sel_hi:[1,0]
	v_pk_mul_f32 v[90:91], v[90:91], v[196:197] op_sel_hi:[1,0]
	v_pk_mul_f32 v[124:125], v[140:141], v[124:125]
	v_pk_mul_f32 v[126:127], v[142:143], v[126:127]
	v_pk_mul_f32 v[120:121], v[136:137], v[120:121]
	v_pk_mul_f32 v[122:123], v[138:139], v[122:123]
	v_pk_mul_f32 v[92:93], v[132:133], v[92:93]
	v_pk_mul_f32 v[94:95], v[134:135], v[94:95]
	v_pk_mul_f32 v[88:89], v[128:129], v[88:89]
	v_pk_mul_f32 v[90:91], v[130:131], v[90:91]
	global_store_dwordx4 v[150:151], v[124:127], off nt
	global_store_dwordx4 v[150:151], v[120:123], off offset:64 nt
	global_store_dwordx4 v[150:151], v[92:95], off offset:512 nt
	global_store_dwordx4 v[150:151], v[88:91], off offset:576 nt
	s_mov_b64 s[88:89], 0x20000
	v_lshl_add_u64 v[162:163], v[150:151], 0, s[88:89]
	v_pk_mul_f32 v[116:117], v[116:117], v[204:205] op_sel_hi:[1,0]
	v_pk_mul_f32 v[118:119], v[118:119], v[204:205] op_sel_hi:[1,0]
	v_pk_mul_f32 v[112:113], v[112:113], v[204:205] op_sel_hi:[1,0]
	v_pk_mul_f32 v[114:115], v[114:115], v[204:205] op_sel_hi:[1,0]
	v_pk_mul_f32 v[84:85], v[84:85], v[204:205] op_sel_hi:[1,0]
	v_pk_mul_f32 v[86:87], v[86:87], v[204:205] op_sel_hi:[1,0]
	v_pk_mul_f32 v[80:81], v[80:81], v[204:205] op_sel_hi:[1,0]
	v_pk_mul_f32 v[82:83], v[82:83], v[204:205] op_sel_hi:[1,0]
	v_pk_mul_f32 v[116:117], v[140:141], v[116:117]
	v_pk_mul_f32 v[118:119], v[142:143], v[118:119]
	v_pk_mul_f32 v[112:113], v[136:137], v[112:113]
	v_pk_mul_f32 v[114:115], v[138:139], v[114:115]
	v_pk_mul_f32 v[84:85], v[132:133], v[84:85]
	v_pk_mul_f32 v[86:87], v[134:135], v[86:87]
	v_pk_mul_f32 v[80:81], v[128:129], v[80:81]
	v_pk_mul_f32 v[82:83], v[130:131], v[82:83]
	global_store_dwordx4 v[162:163], v[116:119], off nt
	global_store_dwordx4 v[162:163], v[112:115], off offset:64 nt
	global_store_dwordx4 v[162:163], v[84:87], off offset:512 nt
	global_store_dwordx4 v[162:163], v[80:83], off offset:576 nt
	s_mov_b64 s[88:89], 0x40000
	v_lshl_add_u64 v[164:165], v[150:151], 0, s[88:89]
	v_pk_mul_f32 v[108:109], v[108:109], v[212:213] op_sel_hi:[1,0]
	v_pk_mul_f32 v[110:111], v[110:111], v[212:213] op_sel_hi:[1,0]
	v_pk_mul_f32 v[104:105], v[104:105], v[212:213] op_sel_hi:[1,0]
	v_pk_mul_f32 v[106:107], v[106:107], v[212:213] op_sel_hi:[1,0]
	v_pk_mul_f32 v[76:77], v[76:77], v[212:213] op_sel_hi:[1,0]
	v_pk_mul_f32 v[78:79], v[78:79], v[212:213] op_sel_hi:[1,0]
	v_pk_mul_f32 v[72:73], v[72:73], v[212:213] op_sel_hi:[1,0]
	v_pk_mul_f32 v[74:75], v[74:75], v[212:213] op_sel_hi:[1,0]
	v_pk_mul_f32 v[108:109], v[140:141], v[108:109]
	v_pk_mul_f32 v[110:111], v[142:143], v[110:111]
	v_pk_mul_f32 v[104:105], v[136:137], v[104:105]
	v_pk_mul_f32 v[106:107], v[138:139], v[106:107]
	v_pk_mul_f32 v[76:77], v[132:133], v[76:77]
	v_pk_mul_f32 v[78:79], v[134:135], v[78:79]
	v_pk_mul_f32 v[72:73], v[128:129], v[72:73]
	v_pk_mul_f32 v[74:75], v[130:131], v[74:75]
	global_store_dwordx4 v[164:165], v[108:111], off nt
	global_store_dwordx4 v[164:165], v[104:107], off offset:64 nt
	global_store_dwordx4 v[164:165], v[76:79], off offset:512 nt
	global_store_dwordx4 v[164:165], v[72:75], off offset:576 nt
	s_mov_b64 s[88:89], 0x60000
	v_lshl_add_u64 v[160:161], v[150:151], 0, s[88:89]
	v_pk_mul_f32 v[100:101], v[100:101], v[220:221] op_sel_hi:[1,0]
	v_pk_mul_f32 v[102:103], v[102:103], v[220:221] op_sel_hi:[1,0]
	v_pk_mul_f32 v[96:97], v[96:97], v[220:221] op_sel_hi:[1,0]
	v_pk_mul_f32 v[98:99], v[98:99], v[220:221] op_sel_hi:[1,0]
	v_pk_mul_f32 v[68:69], v[68:69], v[220:221] op_sel_hi:[1,0]
	v_pk_mul_f32 v[70:71], v[70:71], v[220:221] op_sel_hi:[1,0]
	v_pk_mul_f32 v[64:65], v[64:65], v[220:221] op_sel_hi:[1,0]
	v_pk_mul_f32 v[66:67], v[66:67], v[220:221] op_sel_hi:[1,0]
	v_pk_mul_f32 v[100:101], v[140:141], v[100:101]
	v_pk_mul_f32 v[102:103], v[142:143], v[102:103]
	v_pk_mul_f32 v[96:97], v[136:137], v[96:97]
	v_pk_mul_f32 v[98:99], v[138:139], v[98:99]
	v_pk_mul_f32 v[68:69], v[132:133], v[68:69]
	v_pk_mul_f32 v[70:71], v[134:135], v[70:71]
	v_pk_mul_f32 v[64:65], v[128:129], v[64:65]
	v_pk_mul_f32 v[66:67], v[130:131], v[66:67]
	global_store_dwordx4 v[160:161], v[100:103], off nt
	global_store_dwordx4 v[160:161], v[96:99], off offset:64 nt
;     __device__ __forceinline__ void operator()(f32x4 (&acc)[2][2][4][2], const pg8::Unit& u, int wr, int wc, int fr, int fq) const {
;     ...
; #pragma unroll
;         for (int ai = 0; ai < 2; ++ai)
; #pragma unroll
;             for (int m = 0; m < 4; ++m) {
;                 const int row = row0 + ai * 128 + m * 16;
;                 const f32x4 pa = *(const f32x4*)(ss + (size_t)row * 32 + 8 * fq), pb = *(const f32x4*)(ss + (size_t)row * 32 + 8 * fq + 4);
;                 float sq = ((pa[0] + pa[1]) + (pa[2] + pa[3])) + ((pb[0] + pb[1]) + (pb[2] + pb[3]));
;                 sq += __shfl_xor(sq, 16); sq += __shfl_xor(sq, 32);
;                 const float rinv = __builtin_amdgcn_rsqf(sq * (1.0f / DM) + 1e-6f);
;                 float* orow = oy + (size_t)row * DM + col0;
; #pragma unroll
;                 for (int bj = 0; bj < 2; ++bj)
; #pragma unroll
;                     for (int n = 0; n < 2; ++n) __builtin_nontemporal_store(acc[ai][bj][m][n] * rinv * gg[bj][n], (f32x4*)(orow + bj * 128 + n * 16));
;             }
	global_store_dwordx4 v[160:161], v[68:71], off offset:512 nt
	global_store_dwordx4 v[160:161], v[64:67], off offset:576 nt
	s_mov_b64 s[88:89], 0x100000
	v_lshl_add_u64 v[162:163], v[150:151], 0, s[88:89]
	v_pk_mul_f32 v[60:61], v[60:61], v[228:229] op_sel_hi:[1,0]
	v_pk_mul_f32 v[62:63], v[62:63], v[228:229] op_sel_hi:[1,0]
	v_pk_mul_f32 v[56:57], v[56:57], v[228:229] op_sel_hi:[1,0]
	v_pk_mul_f32 v[58:59], v[58:59], v[228:229] op_sel_hi:[1,0]
	v_pk_mul_f32 v[28:29], v[28:29], v[228:229] op_sel_hi:[1,0]
	v_pk_mul_f32 v[30:31], v[30:31], v[228:229] op_sel_hi:[1,0]
	v_pk_mul_f32 v[24:25], v[24:25], v[228:229] op_sel_hi:[1,0]
	v_pk_mul_f32 v[26:27], v[26:27], v[228:229] op_sel_hi:[1,0]
	v_pk_mul_f32 v[60:61], v[140:141], v[60:61]
	v_pk_mul_f32 v[62:63], v[142:143], v[62:63]
	v_pk_mul_f32 v[56:57], v[136:137], v[56:57]
	v_pk_mul_f32 v[58:59], v[138:139], v[58:59]
	v_pk_mul_f32 v[28:29], v[132:133], v[28:29]
	v_pk_mul_f32 v[30:31], v[134:135], v[30:31]
	v_pk_mul_f32 v[24:25], v[128:129], v[24:25]
	v_pk_mul_f32 v[26:27], v[130:131], v[26:27]
	global_store_dwordx4 v[162:163], v[60:63], off nt
	global_store_dwordx4 v[162:163], v[56:59], off offset:64 nt
	global_store_dwordx4 v[162:163], v[28:31], off offset:512 nt
	global_store_dwordx4 v[162:163], v[24:27], off offset:576 nt
	s_mov_b64 s[88:89], 0x120000
	v_lshl_add_u64 v[164:165], v[150:151], 0, s[88:89]
	v_pk_mul_f32 v[52:53], v[52:53], v[240:241] op_sel_hi:[1,0]
	v_pk_mul_f32 v[54:55], v[54:55], v[240:241] op_sel_hi:[1,0]
	v_pk_mul_f32 v[48:49], v[48:49], v[240:241] op_sel_hi:[1,0]
	v_pk_mul_f32 v[50:51], v[50:51], v[240:241] op_sel_hi:[1,0]
	v_pk_mul_f32 v[20:21], v[20:21], v[240:241] op_sel_hi:[1,0]
	v_pk_mul_f32 v[22:23], v[22:23], v[240:241] op_sel_hi:[1,0]
	v_pk_mul_f32 v[16:17], v[16:17], v[240:241] op_sel_hi:[1,0]
	v_pk_mul_f32 v[18:19], v[18:19], v[240:241] op_sel_hi:[1,0]
	v_pk_mul_f32 v[52:53], v[140:141], v[52:53]
	v_pk_mul_f32 v[54:55], v[142:143], v[54:55]
	v_pk_mul_f32 v[48:49], v[136:137], v[48:49]
	v_pk_mul_f32 v[50:51], v[138:139], v[50:51]
	v_pk_mul_f32 v[20:21], v[132:133], v[20:21]
	v_pk_mul_f32 v[22:23], v[134:135], v[22:23]
	v_pk_mul_f32 v[16:17], v[128:129], v[16:17]
	v_pk_mul_f32 v[18:19], v[130:131], v[18:19]
	global_store_dwordx4 v[164:165], v[52:55], off nt
	global_store_dwordx4 v[164:165], v[48:51], off offset:64 nt
	global_store_dwordx4 v[164:165], v[20:23], off offset:512 nt
	global_store_dwordx4 v[164:165], v[16:19], off offset:576 nt
	s_mov_b64 s[88:89], 0x140000
	v_lshl_add_u64 v[160:161], v[150:151], 0, s[88:89]
	v_pk_mul_f32 v[44:45], v[44:45], v[248:249] op_sel_hi:[1,0]
	v_pk_mul_f32 v[46:47], v[46:47], v[248:249] op_sel_hi:[1,0]
	v_pk_mul_f32 v[40:41], v[40:41], v[248:249] op_sel_hi:[1,0]
	v_pk_mul_f32 v[42:43], v[42:43], v[248:249] op_sel_hi:[1,0]
	v_pk_mul_f32 v[12:13], v[12:13], v[248:249] op_sel_hi:[1,0]
	v_pk_mul_f32 v[14:15], v[14:15], v[248:249] op_sel_hi:[1,0]
	v_pk_mul_f32 v[8:9], v[8:9], v[248:249] op_sel_hi:[1,0]
	v_pk_mul_f32 v[10:11], v[10:11], v[248:249] op_sel_hi:[1,0]
	v_pk_mul_f32 v[44:45], v[140:141], v[44:45]
	v_pk_mul_f32 v[46:47], v[142:143], v[46:47]
	v_pk_mul_f32 v[40:41], v[136:137], v[40:41]
	v_pk_mul_f32 v[42:43], v[138:139], v[42:43]
	v_pk_mul_f32 v[12:13], v[132:133], v[12:13]
	v_pk_mul_f32 v[14:15], v[134:135], v[14:15]
	v_pk_mul_f32 v[8:9], v[128:129], v[8:9]
	v_pk_mul_f32 v[10:11], v[130:131], v[10:11]
	global_store_dwordx4 v[160:161], v[44:47], off nt
	global_store_dwordx4 v[160:161], v[40:43], off offset:64 nt
	global_store_dwordx4 v[160:161], v[12:15], off offset:512 nt
	global_store_dwordx4 v[160:161], v[8:11], off offset:576 nt
	s_mov_b64 s[88:89], 0x160000
	v_lshl_add_u64 v[162:163], v[150:151], 0, s[88:89]
	v_pk_mul_f32 v[36:37], v[36:37], v[152:153] op_sel_hi:[1,0]
	v_pk_mul_f32 v[38:39], v[38:39], v[152:153] op_sel_hi:[1,0]
	v_pk_mul_f32 v[32:33], v[32:33], v[152:153] op_sel_hi:[1,0]
	v_pk_mul_f32 v[34:35], v[34:35], v[152:153] op_sel_hi:[1,0]
	v_pk_mul_f32 v[4:5], v[4:5], v[152:153] op_sel_hi:[1,0]
	v_pk_mul_f32 v[6:7], v[6:7], v[152:153] op_sel_hi:[1,0]
	v_pk_mul_f32 v[0:1], v[0:1], v[152:153] op_sel_hi:[1,0]
	v_pk_mul_f32 v[2:3], v[2:3], v[152:153] op_sel_hi:[1,0]
	v_pk_mul_f32 v[36:37], v[140:141], v[36:37]
	v_pk_mul_f32 v[38:39], v[142:143], v[38:39]
	v_pk_mul_f32 v[32:33], v[136:137], v[32:33]
	v_pk_mul_f32 v[34:35], v[138:139], v[34:35]
	v_pk_mul_f32 v[4:5], v[132:133], v[4:5]
	v_pk_mul_f32 v[6:7], v[134:135], v[6:7]
	v_pk_mul_f32 v[0:1], v[128:129], v[0:1]
	v_pk_mul_f32 v[2:3], v[130:131], v[2:3]
	global_store_dwordx4 v[162:163], v[36:39], off nt
	global_store_dwordx4 v[162:163], v[32:35], off offset:64 nt
	global_store_dwordx4 v[162:163], v[4:7], off offset:512 nt
	global_store_dwordx4 v[162:163], v[0:3], off offset:576 nt
	s_andn2_b64 vcc, exec, s[34:35]
	s_cbranch_vccnz .LBB0_848
	s_andn2_b64 vcc, exec, s[18:19]
	s_cbranch_vccnz .LBB0_847
	s_barrier
	s_branch .LBB0_847
